# v34 plus all dead selects of the scan loader folded away and the loader loop unrolled by 2 with rotated register sets (about 35 fewer VALU instructions per loader iteration)
# speedup vs baseline: 1.0037x; 1.0008x over previous
.Lcib_a_done:
	v_lshlrev_b32_e32 v156, 16, v116
	v_and_b32_e32 v116, 0xffff0000, v116
	v_lshlrev_b32_e32 v178, 16, v117
	v_and_b32_e32 v117, 0xffff0000, v117
	v_lshlrev_b32_e32 v179, 16, v118
	v_and_b32_e32 v118, 0xffff0000, v118
	v_lshlrev_b32_e32 v180, 16, v119
	v_and_b32_e32 v119, 0xffff0000, v119
	v_lshlrev_b32_e32 v162, 16, v112
	v_and_b32_e32 v163, 0xffff0000, v112
	v_lshlrev_b32_e32 v176, 16, v113
	v_and_b32_e32 v177, 0xffff0000, v113
	v_lshlrev_b32_e32 v112, 16, v114
	v_and_b32_e32 v113, 0xffff0000, v114
	v_lshlrev_b32_e32 v114, 16, v115
	v_and_b32_e32 v115, 0xffff0000, v115
	v_mov_b32_e32 v182, v179
	v_sub_f32_e32 v181, v119, v115
	v_sub_f32_e32 v119, v117, v177
	v_sub_f32_e32 v117, v116, v163
	v_sub_f32_e32 v116, v156, v162
	v_sub_f32_e32 v179, v118, v113
	v_sub_f32_e32 v118, v178, v176
	v_sub_f32_e32 v178, v182, v112
	v_sub_f32_e32 v180, v180, v114
	v_pk_fma_f32 v[114:115], v[38:39], v[180:181], v[114:115]
	v_pk_fma_f32 v[112:113], v[36:37], v[178:179], v[112:113]
	v_pk_fma_f32 v[118:119], v[34:35], v[118:119], v[176:177]
	s_and_b64 vcc, exec, s[44:45]
	v_pk_fma_f32 v[116:117], v[32:33], v[116:117], v[162:163]
	s_cbranch_vccnz .Lub_210
	v_lshlrev_b32_e32 v156, 16, v108
	v_and_b32_e32 v108, 0xffff0000, v108
	v_lshlrev_b32_e32 v162, 16, v109
	v_and_b32_e32 v163, 0xffff0000, v109
	v_lshlrev_b32_e32 v176, 16, v110
	v_and_b32_e32 v177, 0xffff0000, v110
	v_lshlrev_b32_e32 v178, 16, v111
	v_and_b32_e32 v179, 0xffff0000, v111
	v_sub_f32_e32 v109, v108, v117
	v_sub_f32_e32 v108, v156, v116
	v_sub_f32_e32 v111, v163, v119
	v_sub_f32_e32 v110, v162, v118
	v_sub_f32_e32 v163, v177, v113
	v_sub_f32_e32 v162, v176, v112
	v_sub_f32_e32 v177, v179, v115
	v_sub_f32_e32 v176, v178, v114
	v_lshlrev_b32_e32 v178, 16, v96
	v_and_b32_e32 v179, 0xffff0000, v96
	v_lshlrev_b32_e32 v96, 16, v97
	v_and_b32_e32 v97, 0xffff0000, v97
	v_lshlrev_b32_e32 v180, 16, v98
	v_and_b32_e32 v181, 0xffff0000, v98
	v_lshlrev_b32_e32 v98, 16, v99
	v_and_b32_e32 v99, 0xffff0000, v99
	v_pk_fma_f32 v[114:115], v[176:177], v[98:99], v[114:115]
	v_pk_fma_f32 v[112:113], v[162:163], v[180:181], v[112:113]
	v_pk_fma_f32 v[118:119], v[110:111], v[96:97], v[118:119]
	v_pk_fma_f32 v[116:117], v[108:109], v[178:179], v[116:117]
.Lub_210:
	v_lshlrev_b32_e32 v163, 16, v86
	v_and_b32_e32 v86, 0xffff0000, v86
	v_lshlrev_b32_e32 v176, 16, v87
	v_and_b32_e32 v87, 0xffff0000, v87
	v_lshlrev_b32_e32 v177, 16, v72
	v_and_b32_e32 v72, 0xffff0000, v72
	v_lshlrev_b32_e32 v178, 16, v73
	v_and_b32_e32 v73, 0xffff0000, v73
	v_lshlrev_b32_e32 v179, 16, v74
	v_and_b32_e32 v74, 0xffff0000, v74
	v_lshlrev_b32_e32 v180, 16, v75
	v_and_b32_e32 v75, 0xffff0000, v75
	v_lshlrev_b32_e32 v98, 16, v82
	v_and_b32_e32 v99, 0xffff0000, v82
	v_lshlrev_b32_e32 v82, 16, v83
	v_and_b32_e32 v83, 0xffff0000, v83
	v_mov_b32_e32 v181, v73
	v_mov_b32_e32 v182, v75
	v_mov_b32_e32 v183, v72
	v_mov_b32_e32 v184, v74
	v_lshlrev_b32_e32 v108, 16, v76
	v_and_b32_e32 v109, 0xffff0000, v76
	v_lshlrev_b32_e32 v110, 16, v78
	v_and_b32_e32 v111, 0xffff0000, v78
	v_sub_f32_e32 v73, v86, v99
	v_sub_f32_e32 v72, v163, v98
	v_sub_f32_e32 v75, v87, v83
	v_sub_f32_e32 v74, v176, v82
	v_lshlrev_b32_e32 v76, 16, v77
	v_and_b32_e32 v77, 0xffff0000, v77
	v_lshlrev_b32_e32 v78, 16, v79
	v_and_b32_e32 v79, 0xffff0000, v79
	v_lshlrev_b32_e32 v162, 16, v85
	v_pk_fma_f32 v[74:75], v[30:31], v[74:75], v[82:83]
	v_pk_fma_f32 v[72:73], v[28:29], v[72:73], v[98:99]
	v_sub_f32_e32 v83, v184, v111
	v_sub_f32_e32 v82, v179, v110
	v_sub_f32_e32 v99, v183, v109
	v_sub_f32_e32 v98, v177, v108
	v_mov_b32_e32 v86, v162
	v_sub_f32_e32 v163, v182, v79
	v_sub_f32_e32 v162, v180, v78
	v_sub_f32_e32 v177, v181, v77
	v_sub_f32_e32 v176, v178, v76
	v_pk_fma_f32 v[108:109], v[24:25], v[98:99], v[108:109]
	v_pk_fma_f32 v[98:99], v[20:21], v[82:83], v[110:111]
	v_pk_fma_f32 v[176:177], v[26:27], v[176:177], v[76:77]
	v_pk_fma_f32 v[162:163], v[22:23], v[162:163], v[78:79]
	v_pk_mul_f32 v[82:83], v[16:17], v[98:99]
	v_pk_mul_f32 v[110:111], v[12:13], v[108:109]
	v_pk_mul_f32 v[178:179], v[18:19], v[162:163]
	v_pk_mul_f32 v[180:181], v[14:15], v[176:177]
	v_pk_mul_f32 v[182:183], v[110:111], v[110:111]
	v_pk_mul_f32 v[184:185], v[82:83], v[82:83]
	v_pk_mul_f32 v[76:77], v[180:181], v[180:181]
	v_pk_mul_f32 v[78:79], v[178:179], v[178:179]
	v_mov_b32_e32 v186, v182
	v_mov_b32_e32 v187, v184
	v_mov_b32_e32 v184, v183
	v_pk_add_f32 v[182:183], v[186:187], v[184:185]
	v_mov_b32_e32 v184, v76
	v_mov_b32_e32 v185, v78
	v_mov_b32_e32 v78, v77
	v_pk_add_f32 v[76:77], v[184:185], v[78:79]
	v_and_b32_e32 v85, 0xffff0000, v85
	v_pk_add_f32 v[76:77], v[182:183], v[76:77]
	v_lshlrev_b32_e32 v96, 16, v80
	v_add_f32_e32 v76, v76, v77
	ds_bpermute_b32 v77, v165, v76
	v_and_b32_e32 v97, 0xffff0000, v80
	v_lshlrev_b32_e32 v80, 16, v81
	v_and_b32_e32 v81, 0xffff0000, v81
	v_lshlrev_b32_e32 v156, 16, v84
	v_and_b32_e32 v84, 0xffff0000, v84
	v_sub_f32_e32 v87, v85, v81
	v_sub_f32_e32 v86, v86, v80
	v_sub_f32_e32 v85, v84, v97
	v_sub_f32_e32 v84, v156, v96
	v_pk_fma_f32 v[86:87], v[10:11], v[86:87], v[80:81]
	v_lshlrev_b32_e32 v81, 16, v52
	v_and_b32_e32 v156, 0xffff0000, v52
	s_waitcnt lgkmcnt(0)
	v_add_f32_e32 v52, v76, v77
	ds_bpermute_b32 v76, v166, v52
	v_lshlrev_b32_e32 v192, 16, v53
	v_and_b32_e32 v193, 0xffff0000, v53
	v_lshlrev_b32_e32 v194, 16, v54
	v_and_b32_e32 v195, 0xffff0000, v54
	s_waitcnt lgkmcnt(0)
	v_add_f32_e32 v52, v52, v76
	ds_bpermute_b32 v53, v167, v52
	v_lshlrev_b32_e32 v202, 16, v55
	v_and_b32_e32 v203, 0xffff0000, v55
	v_lshlrev_b32_e32 v54, 16, v48
	v_and_b32_e32 v55, 0xffff0000, v48
	s_waitcnt lgkmcnt(0)
	v_add_f32_e32 v48, v52, v53
	v_mul_f32_e32 v52, 0x4f800000, v48
	v_cmp_gt_f32_e32 vcc, s76, v48
	v_lshlrev_b32_e32 v184, 16, v50
	v_and_b32_e32 v185, 0xffff0000, v50
	v_cndmask_b32_e32 v52, v48, v52, vcc
	v_sqrt_f32_e32 v53, v52
	v_lshlrev_b32_e32 v182, 16, v51
	v_and_b32_e32 v183, 0xffff0000, v51
	v_lshlrev_b32_e32 v48, 16, v49
	v_add_u32_e32 v76, -1, v53
	v_fma_f32 v77, -v76, v53, v52
	v_cmp_ge_f32_e64 s[48:49], 0, v77
	v_add_u32_e32 v77, 1, v53
	v_and_b32_e32 v49, 0xffff0000, v49
	v_cndmask_b32_e64 v76, v53, v76, s[48:49]
	v_fma_f32 v53, -v77, v53, v52
	v_cmp_lt_f32_e64 s[48:49], 0, v53
	s_bitcmp1_b32 s19, 0
	v_pk_add_f32 v[78:79], v[54:55], -1.0 op_sel_hi:[1,0]
	v_cndmask_b32_e64 v53, v76, v77, s[48:49]
	v_mul_f32_e32 v76, 0x37800000, v53
	v_cndmask_b32_e32 v53, v53, v76, vcc
	v_cmp_class_f32_e32 vcc, v52, v196
	v_pk_fma_f32 v[84:85], v[8:9], v[84:85], v[96:97]
	v_pk_fma_f32 v[96:97], v[4:5], v[78:79], 1.0 op_sel_hi:[1,1,0]
	v_cndmask_b32_e32 v52, v53, v52, vcc
	v_max_f32_e32 v52, 0x2b8cbccc, v52
	v_div_scale_f32 v53, s[22:23], v52, v52, 1.0
	v_rcp_f32_e32 v76, v53
	s_cselect_b32 s22, 0xa800, 0
	v_mul_f32_e32 v78, 0x3fb8aa3b, v202
	v_mul_f32_e32 v79, 0x3fb8aa3b, v203
	v_fma_f32 v50, -v53, v76, 1.0
	v_fmac_f32_e32 v76, v50, v76
	v_div_scale_f32 v50, vcc, 1.0, v52, 1.0
	v_mul_f32_e32 v51, v50, v76
	v_fma_f32 v77, -v53, v51, v50
	v_fmac_f32_e32 v51, v77, v76
	v_fma_f32 v50, -v53, v51, v50
	v_div_fmas_f32 v50, v50, v76, v51
	v_div_fixup_f32 v80, v50, v52, 1.0
	v_pk_add_f32 v[50:51], v[182:183], -1.0 op_sel_hi:[1,0]
	v_pk_add_f32 v[52:53], v[184:185], -1.0 op_sel_hi:[1,0]
	v_pk_add_f32 v[76:77], v[48:49], -1.0 op_sel_hi:[1,0]
	v_pk_fma_f32 v[188:189], v[0:1], v[52:53], 1.0 op_sel_hi:[1,1,0]
	v_pk_fma_f32 v[186:187], v[6:7], v[76:77], 1.0 op_sel_hi:[1,1,0]
	v_pk_fma_f32 v[190:191], v[2:3], v[50:51], 1.0 op_sel_hi:[1,1,0]
	v_mul_f32_e32 v50, 0x3fb8aa3b, v81
	v_mul_f32_e32 v51, 0x3fb8aa3b, v156
	v_mul_f32_e32 v52, 0x3fb8aa3b, v192
	v_mul_f32_e32 v53, 0x3fb8aa3b, v193
	v_mul_f32_e32 v76, 0x3fb8aa3b, v194
	v_mul_f32_e32 v77, 0x3fb8aa3b, v195
	v_pk_mul_f32 v[194:195], v[180:181], v[80:81] op_sel_hi:[1,0]
	v_exp_f32_e32 v50, v50
	v_exp_f32_e32 v51, v51
	v_exp_f32_e32 v52, v52
	v_exp_f32_e32 v53, v53
	v_pk_mul_f32 v[192:193], v[110:111], v[80:81] op_sel_hi:[1,0]
	v_pk_mul_f32 v[180:181], v[82:83], v[80:81] op_sel_hi:[1,0]
	v_pk_mul_f32 v[202:203], v[178:179], v[80:81] op_sel_hi:[1,0]
	v_pk_mul_f32 v[80:81], v[188:189], v[98:99]
	v_pk_mul_f32 v[98:99], v[186:187], v[176:177]
	v_pk_mul_f32 v[186:187], v[194:195], v[48:49]
	v_add_u32_e32 v48, s22, v168
	v_exp_f32_e32 v76, v76
	v_exp_f32_e32 v77, v77
	v_exp_f32_e32 v78, v78
	v_exp_f32_e32 v79, v79
	v_add_u32_e32 v49, v48, v169
	v_pk_mul_f32 v[82:83], v[190:191], v[162:163]
	v_pk_mul_f32 v[96:97], v[96:97], v[108:109]
	v_xor_b32_e32 v111, 0x80000000, v203
	v_xor_b32_e32 v110, 0x80000000, v202
	v_xor_b32_e32 v109, 0x80000000, v181
	v_xor_b32_e32 v108, 0x80000000, v180
	v_xor_b32_e32 v179, 0x80000000, v195
	v_xor_b32_e32 v178, 0x80000000, v194
	v_xor_b32_e32 v177, 0x80000000, v193
	v_xor_b32_e32 v176, 0x80000000, v192
	v_pk_mul_f32 v[182:183], v[202:203], v[182:183]
	v_pk_mul_f32 v[180:181], v[180:181], v[184:185]
	v_pk_mul_f32 v[184:185], v[192:193], v[54:55]
	ds_write_b128 v49, v[84:87]
	ds_write_b128 v49, v[72:75] offset:16
	ds_write_b128 v49, v[50:53] offset:256
	ds_write_b128 v49, v[76:79] offset:272
	ds_write_b128 v49, v[96:99] offset:512
	ds_write_b128 v49, v[80:83] offset:528
	ds_write_b128 v49, v[176:179] offset:768
	ds_write_b128 v49, v[108:111] offset:784
	ds_write_b128 v49, v[184:187] offset:1024
	ds_write_b128 v49, v[180:183] offset:1040
	s_and_saveexec_b64 s[22:23], s[46:47]
	s_cbranch_execz .Lub_212
	v_add_u32_e32 v48, v48, v170
	ds_write_b128 v48, v[116:119] offset:1280
	ds_write_b128 v48, v[112:115] offset:1296
